# plus: residual-add (EpiRes) epilogues of the three out/down projections fetch 7 of the 8 f32 base-tile loads of the next row chunk before the current chunk's FMA and stores (register pool, counted vmc
# speedup vs baseline: 1.0015x; 1.0015x over previous
;     __device__ __forceinline__ void operator()(const Acc& acc, const Unit& u, int wr, int wc, int fr, int fq) const {
;         asm volatile("" : "+v"(fr), "+v"(fq));
;         const int row0 = u.pm * BM + wr * 64 + fr, col0 = u.pn * BM + wc * 32 + 4 * fq;
;         const float* gp = gate + (size_t)(u.pm >> 6) * gate_bstride + col0;
;         f32x4 gv[2][2];
; #pragma unroll
;         for (int bj = 0; bj < 2; ++bj)
; #pragma unroll
;             for (int n = 0; n < 2; ++n) gv[bj][n] = *(const f32x4*)(gp + bj * HALF + n * 16);
; #pragma unroll
;         for (int aim = 0; aim < 4; ++aim) { const int ai = aim >> 1, m0 = (aim & 1) * 2;
;             f32x4 bs[2][2][2];
; #pragma unroll
;             for (int mm = 0; mm < 2; ++mm) { const size_t off = (size_t)(row0 + ai * HALF + (m0 + mm) * 16) * D + col0;
; #pragma unroll
;                 for (int bj = 0; bj < 2; ++bj)
; #pragma unroll
;                     for (int n = 0; n < 2; ++n) bs[mm][bj][n] = *(const f32x4*)(base + off + bj * HALF + n * 16); }
; #pragma unroll
;             for (int mm = 0; mm < 2; ++mm) { const size_t off = (size_t)(row0 + ai * HALF + (m0 + mm) * 16) * D + col0;
; #pragma unroll
;                 for (int bj = 0; bj < 2; ++bj)
; #pragma unroll
;                     for (int n = 0; n < 2; ++n) *(f32x4*)(out + off + bj * HALF + n * 16) = bs[mm][bj][n] + gv[bj][n] * acc[ai][bj][m0 + mm][n]; }
;             asm volatile("" ::: "memory"); }
.LBB0_408:
	v_mov_b32_e32 v64, v172
	v_mov_b32_e32 v168, v159
	s_lshl_b32 s28, s37, 8
	s_or_b32 s28, s28, s9
	v_lshl_add_u32 v64, v64, 2, s28
	s_ashr_i32 s28, s36, 6
	s_mul_hi_i32 s29, s28, 0xc000
	s_mul_i32 s28, s28, 0xc000
	s_add_u32 s28, s6, s28
	v_ashrrev_i32_e32 v65, 31, v64
	s_addc_u32 s29, s7, s29
	v_lshlrev_b64 v[166:167], 2, v[64:65]
	v_lshl_add_u64 v[64:65], s[28:29], 0, v[166:167]
	s_lshl_b32 s28, s36, 8
	s_add_i32 s28, s28, s8
	v_add_u32_e32 v170, s28, v168
	v_readlane_b32 s28, v245, 51
	v_readlane_b32 s29, v245, 52
	v_ashrrev_i32_e32 v171, 31, v170
	v_lshlrev_b64 v[170:171], 13, v[170:171]
	v_lshl_add_u64 v[168:169], s[28:29], 0, v[166:167]
	v_lshl_add_u64 v[180:181], v[168:169], 0, v[170:171]
	s_mov_b64 s[30:31], 0x20000
	global_load_dwordx4 v[108:111], v[64:65], off
	global_load_dwordx4 v[72:75], v[64:65], off offset:64
	global_load_dwordx4 v[68:71], v[64:65], off offset:512
	s_nop 0
	global_load_dwordx4 v[64:67], v[64:65], off offset:576
	s_nop 0
	global_load_dwordx4 v[176:179], v[180:181], off
	global_load_dwordx4 v[192:195], v[180:181], off offset:64
	global_load_dwordx4 v[196:199], v[180:181], off offset:512
	global_load_dwordx4 v[200:203], v[180:181], off offset:576
	v_lshl_add_u64 v[180:181], v[170:171], 0, s[30:31]
	v_lshl_add_u64 v[216:217], v[168:169], 0, v[180:181]
	global_load_dwordx4 v[204:207], v[216:217], off
	global_load_dwordx4 v[208:211], v[216:217], off offset:64
	global_load_dwordx4 v[212:215], v[216:217], off offset:512
	s_nop 0
	global_load_dwordx4 v[216:219], v[216:217], off offset:576
	v_mov_b32_e32 v254, 0x40000
	v_mov_b32_e32 v255, 0
	v_lshl_add_u64 v[232:233], v[170:171], 0, v[254:255]
	v_lshl_add_u64 v[232:233], v[168:169], 0, v[232:233]
	global_load_dwordx4 v[220:223], v[232:233], off
	global_load_dwordx4 v[224:227], v[232:233], off offset:64
	global_load_dwordx4 v[228:231], v[232:233], off offset:512
	s_nop 0
	global_load_dwordx4 v[232:235], v[232:233], off offset:576
	v_mov_b32_e32 v254, 0x60000
	v_lshl_add_u64 v[250:251], v[170:171], 0, v[254:255]
	v_lshl_add_u64 v[250:251], v[168:169], 0, v[250:251]
	global_load_dwordx4 v[236:239], v[250:251], off
	global_load_dwordx4 v[240:243], v[250:251], off offset:64
	s_nop 0
	global_load_dwordx4 v[250:253], v[250:251], off offset:512
	s_mov_b64 s[30:31], 0x40000
	s_andn2_b64 vcc, exec, s[38:39]
	s_waitcnt vmcnt(7)
	v_pk_fma_f32 v[140:141], v[140:141], v[108:109], v[176:177]
	v_lshl_add_u64 v[176:177], s[28:29], 0, v[170:171]
	v_lshl_add_u64 v[176:177], v[176:177], 0, v[166:167]
	v_pk_fma_f32 v[126:127], v[126:127], v[70:71], v[198:199]
	v_pk_fma_f32 v[124:125], v[124:125], v[68:69], v[196:197]
	global_store_dwordx4 v[176:177], v[124:127], off offset:512
	v_pk_fma_f32 v[122:123], v[122:123], v[66:67], v[202:203]
	v_pk_fma_f32 v[120:121], v[120:121], v[64:65], v[200:201]
	v_lshl_add_u64 v[124:125], s[28:29], 0, v[180:181]
	global_store_dwordx4 v[176:177], v[120:123], off offset:576
	v_lshl_add_u64 v[124:125], v[124:125], 0, v[166:167]
	v_pk_fma_f32 v[142:143], v[142:143], v[110:111], v[178:179]
	v_pk_fma_f32 v[122:123], v[134:135], v[110:111], v[206:207]
	v_pk_fma_f32 v[120:121], v[132:133], v[108:109], v[204:205]
	v_pk_fma_f32 v[138:139], v[138:139], v[74:75], v[194:195]
	v_pk_fma_f32 v[136:137], v[136:137], v[72:73], v[192:193]
	global_store_dwordx4 v[124:125], v[120:123], off
	v_pk_fma_f32 v[118:119], v[118:119], v[70:71], v[214:215]
	v_pk_fma_f32 v[116:117], v[116:117], v[68:69], v[212:213]
	v_pk_fma_f32 v[122:123], v[130:131], v[74:75], v[210:211]
	v_pk_fma_f32 v[120:121], v[128:129], v[72:73], v[208:209]
	v_pk_fma_f32 v[114:115], v[114:115], v[66:67], v[218:219]
	v_pk_fma_f32 v[112:113], v[112:113], v[64:65], v[216:217]
	global_store_dwordx4 v[176:177], v[140:143], off
	global_store_dwordx4 v[176:177], v[136:139], off offset:64
	global_store_dwordx4 v[124:125], v[120:123], off offset:64
	global_store_dwordx4 v[124:125], v[116:119], off offset:512
	global_store_dwordx4 v[124:125], v[112:115], off offset:576
	v_lshl_add_u64 v[176:177], v[170:171], 0, s[30:31]
	v_lshl_add_u64 v[124:125], v[168:169], 0, v[176:177]
	s_mov_b64 s[30:31], 0x60000
	s_nop 0
	s_nop 0
	s_nop 0
	s_nop 0
	s_nop 0
	v_lshl_add_u64 v[178:179], v[170:171], 0, s[30:31]
	v_lshl_add_u64 v[140:141], v[168:169], 0, v[178:179]
	s_nop 0
	s_nop 0
	s_nop 0
	s_nop 0
	s_waitcnt vmcnt(8)
;     __device__ __forceinline__ void operator()(const Acc& acc, const Unit& u, int wr, int wc, int fr, int fq) const {
;     ...
;         for (int aim = 0; aim < 4; ++aim) { const int ai = aim >> 1, m0 = (aim & 1) * 2;
;             f32x4 bs[2][2][2];
; #pragma unroll
;             for (int mm = 0; mm < 2; ++mm) { const size_t off = (size_t)(row0 + ai * HALF + (m0 + mm) * 16) * D + col0;
; #pragma unroll
;                 for (int bj = 0; bj < 2; ++bj)
; #pragma unroll
;                     for (int n = 0; n < 2; ++n) bs[mm][bj][n] = *(const f32x4*)(base + off + bj * HALF + n * 16); }
; #pragma unroll
;             for (int mm = 0; mm < 2; ++mm) { const size_t off = (size_t)(row0 + ai * HALF + (m0 + mm) * 16) * D + col0;
; #pragma unroll
;                 for (int bj = 0; bj < 2; ++bj)
; #pragma unroll
;                     for (int n = 0; n < 2; ++n) *(f32x4*)(out + off + bj * HALF + n * 16) = bs[mm][bj][n] + gv[bj][n] * acc[ai][bj][m0 + mm][n]; }
;             asm volatile("" ::: "memory"); }
	v_mov_b32_e32 v112, v220
	v_mov_b32_e32 v113, v221
	v_mov_b32_e32 v114, v222
	v_mov_b32_e32 v115, v223
	v_mov_b32_e32 v116, v224
	v_mov_b32_e32 v117, v225
	v_mov_b32_e32 v118, v226
	v_mov_b32_e32 v119, v227
	v_mov_b32_e32 v120, v228
	v_mov_b32_e32 v121, v229
	v_mov_b32_e32 v122, v230
	v_mov_b32_e32 v123, v231
	v_mov_b32_e32 v124, v232
	v_mov_b32_e32 v125, v233
	v_mov_b32_e32 v126, v234
	v_mov_b32_e32 v127, v235
	v_mov_b32_e32 v128, v236
	v_mov_b32_e32 v129, v237
	v_mov_b32_e32 v130, v238
	v_mov_b32_e32 v131, v239
	v_mov_b32_e32 v132, v240
	v_mov_b32_e32 v133, v241
	v_mov_b32_e32 v134, v242
	v_mov_b32_e32 v135, v243
	v_mov_b32_e32 v136, v250
	v_mov_b32_e32 v137, v251
	v_mov_b32_e32 v138, v252
	v_mov_b32_e32 v139, v253
	global_load_dwordx4 v[140:143], v[140:141], off offset:576
	v_mov_b32_e32 v254, 0x100000
	v_mov_b32_e32 v255, 0
	v_lshl_add_u64 v[232:233], v[170:171], 0, v[254:255]
	v_lshl_add_u64 v[232:233], v[168:169], 0, v[232:233]
	global_load_dwordx4 v[220:223], v[232:233], off
	global_load_dwordx4 v[224:227], v[232:233], off offset:64
	global_load_dwordx4 v[228:231], v[232:233], off offset:512
	s_nop 0
	global_load_dwordx4 v[232:235], v[232:233], off offset:576
	v_mov_b32_e32 v254, 0x120000
	v_lshl_add_u64 v[250:251], v[170:171], 0, v[254:255]
	v_lshl_add_u64 v[250:251], v[168:169], 0, v[250:251]
	global_load_dwordx4 v[236:239], v[250:251], off
	global_load_dwordx4 v[240:243], v[250:251], off offset:64
	s_nop 0
	global_load_dwordx4 v[250:253], v[250:251], off offset:512
	s_mov_b64 s[30:31], 0x100000
	s_nop 0
	v_pk_fma_f32 v[104:105], v[104:105], v[108:109], v[112:113]
	v_lshl_add_u64 v[112:113], s[28:29], 0, v[176:177]
	v_lshl_add_u64 v[112:113], v[112:113], 0, v[166:167]
	s_nop 0
	v_pk_fma_f32 v[90:91], v[90:91], v[70:71], v[122:123]
	v_pk_fma_f32 v[88:89], v[88:89], v[68:69], v[120:121]
	global_store_dwordx4 v[112:113], v[88:91], off offset:512
	s_nop 0
	v_pk_fma_f32 v[86:87], v[86:87], v[66:67], v[126:127]
	v_pk_fma_f32 v[84:85], v[84:85], v[64:65], v[124:125]
	v_lshl_add_u64 v[88:89], s[28:29], 0, v[178:179]
	global_store_dwordx4 v[112:113], v[84:87], off offset:576
	v_lshl_add_u64 v[88:89], v[88:89], 0, v[166:167]
	v_pk_fma_f32 v[106:107], v[106:107], v[110:111], v[114:115]
	s_nop 0
	v_pk_fma_f32 v[86:87], v[98:99], v[110:111], v[130:131]
	v_pk_fma_f32 v[84:85], v[96:97], v[108:109], v[128:129]
	v_pk_fma_f32 v[102:103], v[102:103], v[74:75], v[118:119]
	v_pk_fma_f32 v[100:101], v[100:101], v[72:73], v[116:117]
	global_store_dwordx4 v[88:89], v[84:87], off
	s_nop 0
	v_pk_fma_f32 v[82:83], v[82:83], v[70:71], v[138:139]
	v_pk_fma_f32 v[80:81], v[80:81], v[68:69], v[136:137]
	v_pk_fma_f32 v[86:87], v[94:95], v[74:75], v[134:135]
	v_pk_fma_f32 v[84:85], v[92:93], v[72:73], v[132:133]
	s_waitcnt vmcnt(10)
	v_pk_fma_f32 v[78:79], v[78:79], v[66:67], v[142:143]
	v_pk_fma_f32 v[76:77], v[76:77], v[64:65], v[140:141]
	global_store_dwordx4 v[112:113], v[104:107], off
	global_store_dwordx4 v[112:113], v[100:103], off offset:64
	global_store_dwordx4 v[88:89], v[84:87], off offset:64
	global_store_dwordx4 v[88:89], v[80:83], off offset:512
	global_store_dwordx4 v[88:89], v[76:79], off offset:576
	v_lshl_add_u64 v[112:113], v[170:171], 0, s[30:31]
	v_lshl_add_u64 v[88:89], v[168:169], 0, v[112:113]
	s_mov_b64 s[30:31], 0x120000
	s_nop 0
	s_nop 0
	s_nop 0
	s_nop 0
	s_nop 0
	v_lshl_add_u64 v[114:115], v[170:171], 0, s[30:31]
	v_lshl_add_u64 v[104:105], v[168:169], 0, v[114:115]
	s_nop 0
	s_nop 0
	s_nop 0
	s_nop 0
	s_waitcnt vmcnt(8)
; #define PG8_BAR __builtin_amdgcn_s_barrier()
; template <class Epi, class Map>
; __device__ __forceinline__ void gemm_phase(LAS unsigned char* lds, const Gemm g, const Sched<Map>& S, const Epi& E) {
;     ...
;         if (wr == 0) PG8_BAR;
;         E(acc, cur, wr, wc, fr, fq);
;         if (!has_next) break;
; #pragma unroll
;         for (int a = 0; a < 2; ++a)
; #pragma unroll
;             for (int b = 0; b < 2; ++b)
; #pragma unroll
;                 for (int m = 0; m < 4; ++m)
; #pragma unroll
;                     for (int n = 0; n < 2; ++n) acc[a][b][m][n] = (f32x4){0.f, 0.f, 0.f, 0.f};
;         cur = nxt; cA = nA; cB = nB; ++ui;
;         if (wr == 1) PG8_BAR;
;     __device__ __forceinline__ void operator()(const Acc& acc, const Unit& u, int wr, int wc, int fr, int fq) const {
;     ...
;         for (int aim = 0; aim < 4; ++aim) { const int ai = aim >> 1, m0 = (aim & 1) * 2;
;             f32x4 bs[2][2][2];
; #pragma unroll
;             for (int mm = 0; mm < 2; ++mm) { const size_t off = (size_t)(row0 + ai * HALF + (m0 + mm) * 16) * D + col0;
; #pragma unroll
;                 for (int bj = 0; bj < 2; ++bj)
; #pragma unroll
;                     for (int n = 0; n < 2; ++n) bs[mm][bj][n] = *(const f32x4*)(base + off + bj * HALF + n * 16); }
; #pragma unroll
;             for (int mm = 0; mm < 2; ++mm) { const size_t off = (size_t)(row0 + ai * HALF + (m0 + mm) * 16) * D + col0;
; #pragma unroll
;                 for (int bj = 0; bj < 2; ++bj)
; #pragma unroll
;                     for (int n = 0; n < 2; ++n) *(f32x4*)(out + off + bj * HALF + n * 16) = bs[mm][bj][n] + gv[bj][n] * acc[ai][bj][m0 + mm][n]; }
;             asm volatile("" ::: "memory"); }
	v_mov_b32_e32 v76, v220
	v_mov_b32_e32 v77, v221
	v_mov_b32_e32 v78, v222
	v_mov_b32_e32 v79, v223
	v_mov_b32_e32 v80, v224
	v_mov_b32_e32 v81, v225
	v_mov_b32_e32 v82, v226
	v_mov_b32_e32 v83, v227
	v_mov_b32_e32 v84, v228
	v_mov_b32_e32 v85, v229
	v_mov_b32_e32 v86, v230
	v_mov_b32_e32 v87, v231
	v_mov_b32_e32 v88, v232
	v_mov_b32_e32 v89, v233
	v_mov_b32_e32 v90, v234
	v_mov_b32_e32 v91, v235
	v_mov_b32_e32 v92, v236
	v_mov_b32_e32 v93, v237
	v_mov_b32_e32 v94, v238
	v_mov_b32_e32 v95, v239
	v_mov_b32_e32 v96, v240
	v_mov_b32_e32 v97, v241
	v_mov_b32_e32 v98, v242
	v_mov_b32_e32 v99, v243
	v_mov_b32_e32 v100, v250
	v_mov_b32_e32 v101, v251
	v_mov_b32_e32 v102, v252
	v_mov_b32_e32 v103, v253
	global_load_dwordx4 v[104:107], v[104:105], off offset:576
	v_mov_b32_e32 v254, 0x140000
	v_mov_b32_e32 v255, 0
	v_lshl_add_u64 v[232:233], v[170:171], 0, v[254:255]
	v_lshl_add_u64 v[232:233], v[168:169], 0, v[232:233]
	global_load_dwordx4 v[220:223], v[232:233], off
	global_load_dwordx4 v[224:227], v[232:233], off offset:64
	global_load_dwordx4 v[228:231], v[232:233], off offset:512
	s_nop 0
	global_load_dwordx4 v[232:235], v[232:233], off offset:576
	v_mov_b32_e32 v254, 0x160000
	v_lshl_add_u64 v[250:251], v[170:171], 0, v[254:255]
	v_lshl_add_u64 v[250:251], v[168:169], 0, v[250:251]
	global_load_dwordx4 v[236:239], v[250:251], off
	global_load_dwordx4 v[240:243], v[250:251], off offset:64
	s_nop 0
	global_load_dwordx4 v[250:253], v[250:251], off offset:512
	s_mov_b64 s[30:31], 0x140000
	s_nop 0
	v_pk_fma_f32 v[60:61], v[60:61], v[108:109], v[76:77]
	v_lshl_add_u64 v[76:77], s[28:29], 0, v[112:113]
	v_lshl_add_u64 v[76:77], v[76:77], 0, v[166:167]
	s_nop 0
	v_pk_fma_f32 v[46:47], v[46:47], v[70:71], v[86:87]
	v_pk_fma_f32 v[44:45], v[44:45], v[68:69], v[84:85]
	global_store_dwordx4 v[76:77], v[44:47], off offset:512
	s_nop 0
	v_pk_fma_f32 v[42:43], v[42:43], v[66:67], v[90:91]
	v_pk_fma_f32 v[40:41], v[40:41], v[64:65], v[88:89]
	v_lshl_add_u64 v[44:45], s[28:29], 0, v[114:115]
	global_store_dwordx4 v[76:77], v[40:43], off offset:576
	v_lshl_add_u64 v[44:45], v[44:45], 0, v[166:167]
	v_pk_fma_f32 v[62:63], v[62:63], v[110:111], v[78:79]
	s_nop 0
	v_pk_fma_f32 v[42:43], v[54:55], v[110:111], v[94:95]
	v_pk_fma_f32 v[40:41], v[52:53], v[108:109], v[92:93]
	v_pk_fma_f32 v[58:59], v[58:59], v[74:75], v[82:83]
	v_pk_fma_f32 v[56:57], v[56:57], v[72:73], v[80:81]
	global_store_dwordx4 v[44:45], v[40:43], off
	s_nop 0
	v_pk_fma_f32 v[38:39], v[38:39], v[70:71], v[102:103]
	v_pk_fma_f32 v[36:37], v[36:37], v[68:69], v[100:101]
	v_pk_fma_f32 v[42:43], v[50:51], v[74:75], v[98:99]
	v_pk_fma_f32 v[40:41], v[48:49], v[72:73], v[96:97]
	s_waitcnt vmcnt(10)
	v_pk_fma_f32 v[34:35], v[34:35], v[66:67], v[106:107]
	v_pk_fma_f32 v[32:33], v[32:33], v[64:65], v[104:105]
	global_store_dwordx4 v[76:77], v[60:63], off
	global_store_dwordx4 v[76:77], v[56:59], off offset:64
	global_store_dwordx4 v[44:45], v[40:43], off offset:64
	global_store_dwordx4 v[44:45], v[36:39], off offset:512
	global_store_dwordx4 v[44:45], v[32:35], off offset:576
	v_lshl_add_u64 v[76:77], v[170:171], 0, s[30:31]
	s_mov_b64 s[30:31], 0x160000
	v_lshl_add_u64 v[44:45], v[168:169], 0, v[76:77]
	v_lshl_add_u64 v[78:79], v[170:171], 0, s[30:31]
	s_nop 0
	s_nop 0
	s_nop 0
	s_nop 0
	s_nop 0
	v_lshl_add_u64 v[60:61], v[168:169], 0, v[78:79]
	s_nop 0
	s_nop 0
	s_nop 0
	s_nop 0
	s_waitcnt vmcnt(8)
	v_mov_b32_e32 v32, v220
	v_mov_b32_e32 v33, v221
	v_mov_b32_e32 v34, v222
	v_mov_b32_e32 v35, v223
	v_mov_b32_e32 v36, v224
	v_mov_b32_e32 v37, v225
	v_mov_b32_e32 v38, v226
	v_mov_b32_e32 v39, v227
	v_mov_b32_e32 v40, v228
	v_mov_b32_e32 v41, v229
	v_mov_b32_e32 v42, v230
	v_mov_b32_e32 v43, v231
	v_mov_b32_e32 v44, v232
	v_mov_b32_e32 v45, v233
	v_mov_b32_e32 v46, v234
	v_mov_b32_e32 v47, v235
	v_mov_b32_e32 v48, v236
	v_mov_b32_e32 v49, v237
	v_mov_b32_e32 v50, v238
	v_mov_b32_e32 v51, v239
	v_mov_b32_e32 v52, v240
	v_mov_b32_e32 v53, v241
	v_mov_b32_e32 v54, v242
	v_mov_b32_e32 v55, v243
	v_mov_b32_e32 v56, v250
	v_mov_b32_e32 v57, v251
	v_mov_b32_e32 v58, v252
	v_mov_b32_e32 v59, v253
	global_load_dwordx4 v[60:63], v[60:61], off offset:576
	s_waitcnt vmcnt(7)
	v_pk_fma_f32 v[28:29], v[28:29], v[108:109], v[32:33]
	v_lshl_add_u64 v[32:33], s[28:29], 0, v[76:77]
	v_lshl_add_u64 v[32:33], v[32:33], 0, v[166:167]
	s_waitcnt vmcnt(5)
	v_pk_fma_f32 v[18:19], v[18:19], v[70:71], v[42:43]
	v_pk_fma_f32 v[16:17], v[16:17], v[68:69], v[40:41]
	global_store_dwordx4 v[32:33], v[16:19], off offset:512
	s_waitcnt vmcnt(5)
	v_pk_fma_f32 v[14:15], v[14:15], v[66:67], v[46:47]
	v_pk_fma_f32 v[12:13], v[12:13], v[64:65], v[44:45]
	v_lshl_add_u64 v[16:17], s[28:29], 0, v[78:79]
	v_pk_fma_f32 v[30:31], v[30:31], v[110:111], v[34:35]
	v_pk_fma_f32 v[26:27], v[26:27], v[74:75], v[38:39]
	v_pk_fma_f32 v[24:25], v[24:25], v[72:73], v[36:37]
	global_store_dwordx4 v[32:33], v[12:15], off offset:576
	v_lshl_add_u64 v[16:17], v[16:17], 0, v[166:167]
	s_waitcnt vmcnt(4)
	v_pk_fma_f32 v[10:11], v[10:11], v[74:75], v[54:55]
	v_pk_fma_f32 v[14:15], v[22:23], v[110:111], v[50:51]
	v_pk_fma_f32 v[12:13], v[20:21], v[108:109], v[48:49]
	v_pk_fma_f32 v[8:9], v[8:9], v[72:73], v[52:53]
	s_waitcnt vmcnt(3)
	v_pk_fma_f32 v[6:7], v[6:7], v[70:71], v[58:59]
	v_pk_fma_f32 v[4:5], v[4:5], v[68:69], v[56:57]
	s_waitcnt vmcnt(2)
	v_pk_fma_f32 v[2:3], v[2:3], v[66:67], v[62:63]
	v_pk_fma_f32 v[0:1], v[0:1], v[64:65], v[60:61]
	global_store_dwordx4 v[32:33], v[28:31], off
	global_store_dwordx4 v[32:33], v[24:27], off offset:64
	global_store_dwordx4 v[16:17], v[12:15], off
	global_store_dwordx4 v[16:17], v[8:11], off offset:64
	global_store_dwordx4 v[16:17], v[4:7], off offset:512
	global_store_dwordx4 v[16:17], v[0:3], off offset:576
	s_mov_b64 s[28:29], -1
	s_cbranch_vccnz .LBB0_397
	s_andn2_b64 vcc, exec, s[16:17]
	s_cbranch_vccnz .LBB0_396
	s_barrier
	s_branch .LBB0_396

;     __device__ __forceinline__ void operator()(const Acc& acc, const Unit& u, int wr, int wc, int fr, int fq) const {
;         asm volatile("" : "+v"(fr), "+v"(fq));
;         const int row0 = u.pm * BM + wr * 64 + fr, col0 = u.pn * BM + wc * 32 + 4 * fq;
;         const float* gp = gate + (size_t)(u.pm >> 6) * gate_bstride + col0;
;         f32x4 gv[2][2];
; #pragma unroll
;         for (int bj = 0; bj < 2; ++bj)
; #pragma unroll
;             for (int n = 0; n < 2; ++n) gv[bj][n] = *(const f32x4*)(gp + bj * HALF + n * 16);
; #pragma unroll
;         for (int aim = 0; aim < 4; ++aim) { const int ai = aim >> 1, m0 = (aim & 1) * 2;
;             f32x4 bs[2][2][2];
; #pragma unroll
;             for (int mm = 0; mm < 2; ++mm) { const size_t off = (size_t)(row0 + ai * HALF + (m0 + mm) * 16) * D + col0;
; #pragma unroll
;                 for (int bj = 0; bj < 2; ++bj)
; #pragma unroll
;                     for (int n = 0; n < 2; ++n) bs[mm][bj][n] = *(const f32x4*)(base + off + bj * HALF + n * 16); }
; #pragma unroll
;             for (int mm = 0; mm < 2; ++mm) { const size_t off = (size_t)(row0 + ai * HALF + (m0 + mm) * 16) * D + col0;
; #pragma unroll
;                 for (int bj = 0; bj < 2; ++bj)
; #pragma unroll
;                     for (int n = 0; n < 2; ++n) *(f32x4*)(out + off + bj * HALF + n * 16) = bs[mm][bj][n] + gv[bj][n] * acc[ai][bj][m0 + mm][n]; }
;             asm volatile("" ::: "memory"); }
.LBB0_955:
	v_mov_b32_e32 v168, v159
	v_mov_b32_e32 v64, v172
	s_lshl_b32 s15, s15, 8
	s_or_b32 s15, s15, s6
	s_lshl_b32 s14, s14, 8
	v_lshl_add_u32 v64, v64, 2, s15
	s_add_i32 s14, s14, s5
	v_ashrrev_i32_e32 v65, 31, v64
	v_add_u32_e32 v170, s14, v168
	v_lshlrev_b64 v[166:167], 2, v[64:65]
	v_ashrrev_i32_e32 v171, 31, v170
	v_lshl_add_u64 v[168:169], s[18:19], 0, v[166:167]
	v_lshlrev_b64 v[170:171], 13, v[170:171]
	v_lshl_add_u64 v[64:65], s[24:25], 0, v[166:167]
	v_lshl_add_u64 v[180:181], v[168:169], 0, v[170:171]
	s_mov_b64 s[14:15], 0x20000
	global_load_dwordx4 v[108:111], v[64:65], off
	global_load_dwordx4 v[72:75], v[64:65], off offset:64
	global_load_dwordx4 v[68:71], v[64:65], off offset:512
	s_nop 0
	global_load_dwordx4 v[64:67], v[64:65], off offset:576
	s_nop 0
	global_load_dwordx4 v[176:179], v[180:181], off
	global_load_dwordx4 v[192:195], v[180:181], off offset:64
	global_load_dwordx4 v[196:199], v[180:181], off offset:512
	global_load_dwordx4 v[200:203], v[180:181], off offset:576
	v_lshl_add_u64 v[180:181], v[170:171], 0, s[14:15]
	v_lshl_add_u64 v[216:217], v[168:169], 0, v[180:181]
	global_load_dwordx4 v[204:207], v[216:217], off
	global_load_dwordx4 v[208:211], v[216:217], off offset:64
	global_load_dwordx4 v[212:215], v[216:217], off offset:512
	s_nop 0
	global_load_dwordx4 v[216:219], v[216:217], off offset:576
	v_mov_b32_e32 v254, 0x40000
	v_mov_b32_e32 v255, 0
	v_lshl_add_u64 v[232:233], v[170:171], 0, v[254:255]
	v_lshl_add_u64 v[232:233], v[168:169], 0, v[232:233]
	global_load_dwordx4 v[220:223], v[232:233], off
	global_load_dwordx4 v[224:227], v[232:233], off offset:64
	global_load_dwordx4 v[228:231], v[232:233], off offset:512
	s_nop 0
	global_load_dwordx4 v[232:235], v[232:233], off offset:576
	v_mov_b32_e32 v254, 0x60000
	v_lshl_add_u64 v[250:251], v[170:171], 0, v[254:255]
	v_lshl_add_u64 v[250:251], v[168:169], 0, v[250:251]
	global_load_dwordx4 v[236:239], v[250:251], off
	global_load_dwordx4 v[240:243], v[250:251], off offset:64
	s_nop 0
	global_load_dwordx4 v[250:253], v[250:251], off offset:512
	s_mov_b64 s[14:15], 0x40000
	s_mov_b64 s[36:37], -1
	s_andn2_b64 vcc, exec, s[38:39]
	s_waitcnt vmcnt(7)
	v_pk_fma_f32 v[140:141], v[140:141], v[108:109], v[176:177]
	v_lshl_add_u64 v[176:177], s[20:21], 0, v[170:171]
	v_lshl_add_u64 v[176:177], v[176:177], 0, v[166:167]
	v_pk_fma_f32 v[126:127], v[126:127], v[70:71], v[198:199]
	v_pk_fma_f32 v[124:125], v[124:125], v[68:69], v[196:197]
	global_store_dwordx4 v[176:177], v[124:127], off offset:512
	v_pk_fma_f32 v[122:123], v[122:123], v[66:67], v[202:203]
	v_pk_fma_f32 v[120:121], v[120:121], v[64:65], v[200:201]
	v_lshl_add_u64 v[124:125], s[20:21], 0, v[180:181]
	global_store_dwordx4 v[176:177], v[120:123], off offset:576
	v_lshl_add_u64 v[124:125], v[124:125], 0, v[166:167]
	v_pk_fma_f32 v[142:143], v[142:143], v[110:111], v[178:179]
	v_pk_fma_f32 v[122:123], v[134:135], v[110:111], v[206:207]
	v_pk_fma_f32 v[120:121], v[132:133], v[108:109], v[204:205]
	v_pk_fma_f32 v[138:139], v[138:139], v[74:75], v[194:195]
	v_pk_fma_f32 v[136:137], v[136:137], v[72:73], v[192:193]
	global_store_dwordx4 v[124:125], v[120:123], off
	v_pk_fma_f32 v[118:119], v[118:119], v[70:71], v[214:215]
	v_pk_fma_f32 v[116:117], v[116:117], v[68:69], v[212:213]
	v_pk_fma_f32 v[122:123], v[130:131], v[74:75], v[210:211]
	v_pk_fma_f32 v[120:121], v[128:129], v[72:73], v[208:209]
	v_pk_fma_f32 v[114:115], v[114:115], v[66:67], v[218:219]
	v_pk_fma_f32 v[112:113], v[112:113], v[64:65], v[216:217]
	global_store_dwordx4 v[176:177], v[140:143], off
	global_store_dwordx4 v[176:177], v[136:139], off offset:64
	global_store_dwordx4 v[124:125], v[120:123], off offset:64
	global_store_dwordx4 v[124:125], v[116:119], off offset:512
	global_store_dwordx4 v[124:125], v[112:115], off offset:576
	v_lshl_add_u64 v[176:177], v[170:171], 0, s[14:15]
	v_lshl_add_u64 v[124:125], v[168:169], 0, v[176:177]
	s_mov_b64 s[14:15], 0x60000
	s_nop 0
	s_nop 0
	s_nop 0
	s_nop 0
	s_nop 0
	v_lshl_add_u64 v[178:179], v[170:171], 0, s[14:15]
	v_lshl_add_u64 v[140:141], v[168:169], 0, v[178:179]
	s_nop 0
	s_nop 0
	s_nop 0
	s_nop 0
	s_waitcnt vmcnt(8)
	v_mov_b32_e32 v112, v220
	v_mov_b32_e32 v113, v221
	v_mov_b32_e32 v114, v222
	v_mov_b32_e32 v115, v223
	v_mov_b32_e32 v116, v224
	v_mov_b32_e32 v117, v225
	v_mov_b32_e32 v118, v226
	v_mov_b32_e32 v119, v227
	v_mov_b32_e32 v120, v228
	v_mov_b32_e32 v121, v229
	v_mov_b32_e32 v122, v230
	v_mov_b32_e32 v123, v231
	v_mov_b32_e32 v124, v232
	v_mov_b32_e32 v125, v233
	v_mov_b32_e32 v126, v234
	v_mov_b32_e32 v127, v235
	v_mov_b32_e32 v128, v236
	v_mov_b32_e32 v129, v237
	v_mov_b32_e32 v130, v238
	v_mov_b32_e32 v131, v239
	v_mov_b32_e32 v132, v240
	v_mov_b32_e32 v133, v241
	v_mov_b32_e32 v134, v242
	v_mov_b32_e32 v135, v243
	v_mov_b32_e32 v136, v250
	v_mov_b32_e32 v137, v251
	v_mov_b32_e32 v138, v252
	v_mov_b32_e32 v139, v253
	global_load_dwordx4 v[140:143], v[140:141], off offset:576
	v_mov_b32_e32 v254, 0x100000
	v_mov_b32_e32 v255, 0
	v_lshl_add_u64 v[232:233], v[170:171], 0, v[254:255]
	v_lshl_add_u64 v[232:233], v[168:169], 0, v[232:233]
	global_load_dwordx4 v[220:223], v[232:233], off
	global_load_dwordx4 v[224:227], v[232:233], off offset:64
	global_load_dwordx4 v[228:231], v[232:233], off offset:512
	s_nop 0
	global_load_dwordx4 v[232:235], v[232:233], off offset:576
	v_mov_b32_e32 v254, 0x120000
	v_lshl_add_u64 v[250:251], v[170:171], 0, v[254:255]
	v_lshl_add_u64 v[250:251], v[168:169], 0, v[250:251]
	global_load_dwordx4 v[236:239], v[250:251], off
	global_load_dwordx4 v[240:243], v[250:251], off offset:64
	s_nop 0
	global_load_dwordx4 v[250:253], v[250:251], off offset:512
	s_mov_b64 s[14:15], 0x100000
	s_nop 0
	v_pk_fma_f32 v[104:105], v[104:105], v[108:109], v[112:113]
	v_lshl_add_u64 v[112:113], s[20:21], 0, v[176:177]
	v_lshl_add_u64 v[112:113], v[112:113], 0, v[166:167]
	s_nop 0
	v_pk_fma_f32 v[90:91], v[90:91], v[70:71], v[122:123]
	v_pk_fma_f32 v[88:89], v[88:89], v[68:69], v[120:121]
	global_store_dwordx4 v[112:113], v[88:91], off offset:512
	s_nop 0
	v_pk_fma_f32 v[86:87], v[86:87], v[66:67], v[126:127]
	v_pk_fma_f32 v[84:85], v[84:85], v[64:65], v[124:125]
	v_lshl_add_u64 v[88:89], s[20:21], 0, v[178:179]
	global_store_dwordx4 v[112:113], v[84:87], off offset:576
	v_lshl_add_u64 v[88:89], v[88:89], 0, v[166:167]
	v_pk_fma_f32 v[106:107], v[106:107], v[110:111], v[114:115]
	s_nop 0
	v_pk_fma_f32 v[86:87], v[98:99], v[110:111], v[130:131]
	v_pk_fma_f32 v[84:85], v[96:97], v[108:109], v[128:129]
	v_pk_fma_f32 v[102:103], v[102:103], v[74:75], v[118:119]
	v_pk_fma_f32 v[100:101], v[100:101], v[72:73], v[116:117]
	global_store_dwordx4 v[88:89], v[84:87], off
	s_nop 0
	v_pk_fma_f32 v[82:83], v[82:83], v[70:71], v[138:139]
	v_pk_fma_f32 v[80:81], v[80:81], v[68:69], v[136:137]
	v_pk_fma_f32 v[86:87], v[94:95], v[74:75], v[134:135]
	v_pk_fma_f32 v[84:85], v[92:93], v[72:73], v[132:133]
	s_waitcnt vmcnt(10)
; #define PG8_BAR __builtin_amdgcn_s_barrier()
; template <class Epi, class Map>
; __device__ __forceinline__ void gemm_phase(LAS unsigned char* lds, const Gemm g, const Sched<Map>& S, const Epi& E) {
;     ...
;         if (wr == 0) PG8_BAR;
;         E(acc, cur, wr, wc, fr, fq);
;         if (!has_next) break;
; #pragma unroll
;         for (int a = 0; a < 2; ++a)
; #pragma unroll
;             for (int b = 0; b < 2; ++b)
; #pragma unroll
;                 for (int m = 0; m < 4; ++m)
; #pragma unroll
;                     for (int n = 0; n < 2; ++n) acc[a][b][m][n] = (f32x4){0.f, 0.f, 0.f, 0.f};
;         cur = nxt; cA = nA; cB = nB; ++ui;
;         if (wr == 1) PG8_BAR;
;     __device__ __forceinline__ void operator()(const Acc& acc, const Unit& u, int wr, int wc, int fr, int fq) const {
;     ...
;         for (int aim = 0; aim < 4; ++aim) { const int ai = aim >> 1, m0 = (aim & 1) * 2;
;             f32x4 bs[2][2][2];
; #pragma unroll
;             for (int mm = 0; mm < 2; ++mm) { const size_t off = (size_t)(row0 + ai * HALF + (m0 + mm) * 16) * D + col0;
; #pragma unroll
;                 for (int bj = 0; bj < 2; ++bj)
; #pragma unroll
;                     for (int n = 0; n < 2; ++n) bs[mm][bj][n] = *(const f32x4*)(base + off + bj * HALF + n * 16); }
; #pragma unroll
;             for (int mm = 0; mm < 2; ++mm) { const size_t off = (size_t)(row0 + ai * HALF + (m0 + mm) * 16) * D + col0;
; #pragma unroll
;                 for (int bj = 0; bj < 2; ++bj)
; #pragma unroll
;                     for (int n = 0; n < 2; ++n) *(f32x4*)(out + off + bj * HALF + n * 16) = bs[mm][bj][n] + gv[bj][n] * acc[ai][bj][m0 + mm][n]; }
;             asm volatile("" ::: "memory"); }
	v_pk_fma_f32 v[78:79], v[78:79], v[66:67], v[142:143]
	v_pk_fma_f32 v[76:77], v[76:77], v[64:65], v[140:141]
	global_store_dwordx4 v[112:113], v[104:107], off
	global_store_dwordx4 v[112:113], v[100:103], off offset:64
	global_store_dwordx4 v[88:89], v[84:87], off offset:64
	global_store_dwordx4 v[88:89], v[80:83], off offset:512
	global_store_dwordx4 v[88:89], v[76:79], off offset:576
	v_lshl_add_u64 v[112:113], v[170:171], 0, s[14:15]
	v_lshl_add_u64 v[88:89], v[168:169], 0, v[112:113]
	s_mov_b64 s[14:15], 0x120000
	s_nop 0
	s_nop 0
	s_nop 0
	s_nop 0
	s_nop 0
	v_lshl_add_u64 v[114:115], v[170:171], 0, s[14:15]
	v_lshl_add_u64 v[104:105], v[168:169], 0, v[114:115]
	s_nop 0
	s_nop 0
	s_nop 0
	s_nop 0
	s_waitcnt vmcnt(8)
	v_mov_b32_e32 v76, v220
	v_mov_b32_e32 v77, v221
	v_mov_b32_e32 v78, v222
	v_mov_b32_e32 v79, v223
	v_mov_b32_e32 v80, v224
	v_mov_b32_e32 v81, v225
	v_mov_b32_e32 v82, v226
	v_mov_b32_e32 v83, v227
	v_mov_b32_e32 v84, v228
	v_mov_b32_e32 v85, v229
	v_mov_b32_e32 v86, v230
	v_mov_b32_e32 v87, v231
	v_mov_b32_e32 v88, v232
	v_mov_b32_e32 v89, v233
	v_mov_b32_e32 v90, v234
	v_mov_b32_e32 v91, v235
	v_mov_b32_e32 v92, v236
	v_mov_b32_e32 v93, v237
	v_mov_b32_e32 v94, v238
	v_mov_b32_e32 v95, v239
	v_mov_b32_e32 v96, v240
	v_mov_b32_e32 v97, v241
	v_mov_b32_e32 v98, v242
	v_mov_b32_e32 v99, v243
	v_mov_b32_e32 v100, v250
	v_mov_b32_e32 v101, v251
	v_mov_b32_e32 v102, v252
	v_mov_b32_e32 v103, v253
	global_load_dwordx4 v[104:107], v[104:105], off offset:576
	v_mov_b32_e32 v254, 0x140000
	v_mov_b32_e32 v255, 0
	v_lshl_add_u64 v[232:233], v[170:171], 0, v[254:255]
	v_lshl_add_u64 v[232:233], v[168:169], 0, v[232:233]
	global_load_dwordx4 v[220:223], v[232:233], off
	global_load_dwordx4 v[224:227], v[232:233], off offset:64
	global_load_dwordx4 v[228:231], v[232:233], off offset:512
	s_nop 0
	global_load_dwordx4 v[232:235], v[232:233], off offset:576
	v_mov_b32_e32 v254, 0x160000
	v_lshl_add_u64 v[250:251], v[170:171], 0, v[254:255]
	v_lshl_add_u64 v[250:251], v[168:169], 0, v[250:251]
	global_load_dwordx4 v[236:239], v[250:251], off
	global_load_dwordx4 v[240:243], v[250:251], off offset:64
	s_nop 0
	global_load_dwordx4 v[250:253], v[250:251], off offset:512
	s_mov_b64 s[14:15], 0x140000
	s_nop 0
	v_pk_fma_f32 v[60:61], v[60:61], v[108:109], v[76:77]
	v_lshl_add_u64 v[76:77], s[20:21], 0, v[112:113]
	v_lshl_add_u64 v[76:77], v[76:77], 0, v[166:167]
	s_nop 0
	v_pk_fma_f32 v[46:47], v[46:47], v[70:71], v[86:87]
	v_pk_fma_f32 v[44:45], v[44:45], v[68:69], v[84:85]
	global_store_dwordx4 v[76:77], v[44:47], off offset:512
	s_nop 0
	v_pk_fma_f32 v[42:43], v[42:43], v[66:67], v[90:91]
	v_pk_fma_f32 v[40:41], v[40:41], v[64:65], v[88:89]
	v_lshl_add_u64 v[44:45], s[20:21], 0, v[114:115]
	global_store_dwordx4 v[76:77], v[40:43], off offset:576
	v_lshl_add_u64 v[44:45], v[44:45], 0, v[166:167]
	v_pk_fma_f32 v[62:63], v[62:63], v[110:111], v[78:79]
	s_nop 0
	v_pk_fma_f32 v[42:43], v[54:55], v[110:111], v[94:95]
	v_pk_fma_f32 v[40:41], v[52:53], v[108:109], v[92:93]
	v_pk_fma_f32 v[58:59], v[58:59], v[74:75], v[82:83]
	v_pk_fma_f32 v[56:57], v[56:57], v[72:73], v[80:81]
	global_store_dwordx4 v[44:45], v[40:43], off
	s_nop 0
	v_pk_fma_f32 v[38:39], v[38:39], v[70:71], v[102:103]
	v_pk_fma_f32 v[36:37], v[36:37], v[68:69], v[100:101]
	v_pk_fma_f32 v[42:43], v[50:51], v[74:75], v[98:99]
	v_pk_fma_f32 v[40:41], v[48:49], v[72:73], v[96:97]
	s_waitcnt vmcnt(10)
	v_pk_fma_f32 v[34:35], v[34:35], v[66:67], v[106:107]
	v_pk_fma_f32 v[32:33], v[32:33], v[64:65], v[104:105]
	global_store_dwordx4 v[76:77], v[60:63], off
	global_store_dwordx4 v[76:77], v[56:59], off offset:64
	global_store_dwordx4 v[44:45], v[40:43], off offset:64
	global_store_dwordx4 v[44:45], v[36:39], off offset:512
	global_store_dwordx4 v[44:45], v[32:35], off offset:576
	v_lshl_add_u64 v[76:77], v[170:171], 0, s[14:15]
	s_mov_b64 s[14:15], 0x160000
	v_lshl_add_u64 v[44:45], v[168:169], 0, v[76:77]
	v_lshl_add_u64 v[78:79], v[170:171], 0, s[14:15]
	s_nop 0
	s_nop 0
	s_nop 0
	s_nop 0
	s_nop 0
	v_lshl_add_u64 v[60:61], v[168:169], 0, v[78:79]
	s_nop 0
	s_nop 0
	s_nop 0
	s_nop 0
	s_waitcnt vmcnt(8)
	v_mov_b32_e32 v32, v220
	v_mov_b32_e32 v33, v221
	v_mov_b32_e32 v34, v222
	v_mov_b32_e32 v35, v223
	v_mov_b32_e32 v36, v224
	v_mov_b32_e32 v37, v225
	v_mov_b32_e32 v38, v226
	v_mov_b32_e32 v39, v227
	v_mov_b32_e32 v40, v228
	v_mov_b32_e32 v41, v229
	v_mov_b32_e32 v42, v230
	v_mov_b32_e32 v43, v231
	v_mov_b32_e32 v44, v232
	v_mov_b32_e32 v45, v233
	v_mov_b32_e32 v46, v234
	v_mov_b32_e32 v47, v235
	v_mov_b32_e32 v48, v236
	v_mov_b32_e32 v49, v237
	v_mov_b32_e32 v50, v238
	v_mov_b32_e32 v51, v239
	v_mov_b32_e32 v52, v240
	v_mov_b32_e32 v53, v241
	v_mov_b32_e32 v54, v242
	v_mov_b32_e32 v55, v243
	v_mov_b32_e32 v56, v250
	v_mov_b32_e32 v57, v251
	v_mov_b32_e32 v58, v252
	v_mov_b32_e32 v59, v253
	global_load_dwordx4 v[60:63], v[60:61], off offset:576
	s_waitcnt vmcnt(7)
	v_pk_fma_f32 v[28:29], v[28:29], v[108:109], v[32:33]
	v_lshl_add_u64 v[32:33], s[20:21], 0, v[76:77]
	v_lshl_add_u64 v[32:33], v[32:33], 0, v[166:167]
	s_waitcnt vmcnt(5)
	v_pk_fma_f32 v[18:19], v[18:19], v[70:71], v[42:43]
	v_pk_fma_f32 v[16:17], v[16:17], v[68:69], v[40:41]
	global_store_dwordx4 v[32:33], v[16:19], off offset:512
	s_waitcnt vmcnt(5)
	v_pk_fma_f32 v[14:15], v[14:15], v[66:67], v[46:47]
	v_pk_fma_f32 v[12:13], v[12:13], v[64:65], v[44:45]
	v_lshl_add_u64 v[16:17], s[20:21], 0, v[78:79]
	v_pk_fma_f32 v[30:31], v[30:31], v[110:111], v[34:35]
	v_pk_fma_f32 v[26:27], v[26:27], v[74:75], v[38:39]
	v_pk_fma_f32 v[24:25], v[24:25], v[72:73], v[36:37]
	global_store_dwordx4 v[32:33], v[12:15], off offset:576
	v_lshl_add_u64 v[16:17], v[16:17], 0, v[166:167]
	s_waitcnt vmcnt(4)
	v_pk_fma_f32 v[10:11], v[10:11], v[74:75], v[54:55]
	v_pk_fma_f32 v[14:15], v[22:23], v[110:111], v[50:51]
	v_pk_fma_f32 v[12:13], v[20:21], v[108:109], v[48:49]
	v_pk_fma_f32 v[8:9], v[8:9], v[72:73], v[52:53]
	s_waitcnt vmcnt(3)
	v_pk_fma_f32 v[6:7], v[6:7], v[70:71], v[58:59]
	v_pk_fma_f32 v[4:5], v[4:5], v[68:69], v[56:57]
	s_waitcnt vmcnt(2)
	v_pk_fma_f32 v[2:3], v[2:3], v[66:67], v[62:63]
	v_pk_fma_f32 v[0:1], v[0:1], v[64:65], v[60:61]
	global_store_dwordx4 v[32:33], v[28:31], off
	global_store_dwordx4 v[32:33], v[24:27], off offset:64
	global_store_dwordx4 v[16:17], v[12:15], off
	global_store_dwordx4 v[16:17], v[8:11], off offset:64
	global_store_dwordx4 v[16:17], v[4:7], off offset:512
	global_store_dwordx4 v[16:17], v[0:3], off offset:576
	s_cbranch_vccnz .LBB0_944
	s_andn2_b64 vcc, exec, s[16:17]
	s_cbranch_vccnz .LBB0_943
	s_barrier
	s_branch .LBB0_943

;     __device__ __forceinline__ void operator()(const Acc& acc, const Unit& u, int wr, int wc, int fr, int fq) const {
;         asm volatile("" : "+v"(fr), "+v"(fq));
;         const int row0 = u.pm * BM + wr * 64 + fr, col0 = u.pn * BM + wc * 32 + 4 * fq;
;         const float* gp = gate + (size_t)(u.pm >> 6) * gate_bstride + col0;
;         f32x4 gv[2][2];
; #pragma unroll
;         for (int bj = 0; bj < 2; ++bj)
; #pragma unroll
;             for (int n = 0; n < 2; ++n) gv[bj][n] = *(const f32x4*)(gp + bj * HALF + n * 16);
; #pragma unroll
;         for (int aim = 0; aim < 4; ++aim) { const int ai = aim >> 1, m0 = (aim & 1) * 2;
;             f32x4 bs[2][2][2];
; #pragma unroll
;             for (int mm = 0; mm < 2; ++mm) { const size_t off = (size_t)(row0 + ai * HALF + (m0 + mm) * 16) * D + col0;
; #pragma unroll
;                 for (int bj = 0; bj < 2; ++bj)
; #pragma unroll
;                     for (int n = 0; n < 2; ++n) bs[mm][bj][n] = *(const f32x4*)(base + off + bj * HALF + n * 16); }
; #pragma unroll
;             for (int mm = 0; mm < 2; ++mm) { const size_t off = (size_t)(row0 + ai * HALF + (m0 + mm) * 16) * D + col0;
; #pragma unroll
;                 for (int bj = 0; bj < 2; ++bj)
; #pragma unroll
;                     for (int n = 0; n < 2; ++n) *(f32x4*)(out + off + bj * HALF + n * 16) = bs[mm][bj][n] + gv[bj][n] * acc[ai][bj][m0 + mm][n]; }
;             asm volatile("" ::: "memory"); }
.LBB0_1186:
	v_mov_b32_e32 v168, v159
	v_mov_b32_e32 v64, v172
	s_lshl_b32 s28, s36, 8
	s_or_b32 s28, s28, s8
	v_lshl_add_u32 v64, v64, 2, s28
	s_ashr_i32 s28, s33, 6
	s_mul_hi_i32 s29, s28, 0xc000
	s_mul_i32 s28, s28, 0xc000
	s_add_u32 s28, s0, s28
	v_ashrrev_i32_e32 v65, 31, v64
	s_addc_u32 s29, s1, s29
	v_lshlrev_b64 v[166:167], 2, v[64:65]
	v_lshl_add_u64 v[64:65], s[28:29], 0, v[166:167]
	s_lshl_b32 s28, s33, 8
	s_add_i32 s28, s28, s7
	v_add_u32_e32 v170, s28, v168
	v_readlane_b32 s28, v245, 51
	v_readlane_b32 s29, v245, 52
	v_ashrrev_i32_e32 v171, 31, v170
	v_lshlrev_b64 v[170:171], 13, v[170:171]
	v_lshl_add_u64 v[168:169], s[28:29], 0, v[166:167]
	v_lshl_add_u64 v[180:181], v[168:169], 0, v[170:171]
	s_mov_b64 s[30:31], 0x20000
	global_load_dwordx4 v[108:111], v[64:65], off
	global_load_dwordx4 v[72:75], v[64:65], off offset:64
	global_load_dwordx4 v[68:71], v[64:65], off offset:512
	s_nop 0
	global_load_dwordx4 v[64:67], v[64:65], off offset:576
	s_nop 0
	global_load_dwordx4 v[176:179], v[180:181], off
	global_load_dwordx4 v[192:195], v[180:181], off offset:64
	global_load_dwordx4 v[196:199], v[180:181], off offset:512
	global_load_dwordx4 v[200:203], v[180:181], off offset:576
	v_lshl_add_u64 v[180:181], v[170:171], 0, s[30:31]
	v_lshl_add_u64 v[216:217], v[168:169], 0, v[180:181]
	global_load_dwordx4 v[204:207], v[216:217], off
	global_load_dwordx4 v[208:211], v[216:217], off offset:64
	global_load_dwordx4 v[212:215], v[216:217], off offset:512
	s_nop 0
	global_load_dwordx4 v[216:219], v[216:217], off offset:576
	v_mov_b32_e32 v254, 0x40000
	v_mov_b32_e32 v255, 0
	v_lshl_add_u64 v[232:233], v[170:171], 0, v[254:255]
	v_lshl_add_u64 v[232:233], v[168:169], 0, v[232:233]
	global_load_dwordx4 v[220:223], v[232:233], off
	global_load_dwordx4 v[224:227], v[232:233], off offset:64
	global_load_dwordx4 v[228:231], v[232:233], off offset:512
	s_nop 0
	global_load_dwordx4 v[232:235], v[232:233], off offset:576
	v_mov_b32_e32 v254, 0x60000
	v_lshl_add_u64 v[250:251], v[170:171], 0, v[254:255]
	v_lshl_add_u64 v[250:251], v[168:169], 0, v[250:251]
	global_load_dwordx4 v[236:239], v[250:251], off
	global_load_dwordx4 v[240:243], v[250:251], off offset:64
	s_nop 0
	global_load_dwordx4 v[250:253], v[250:251], off offset:512
	s_mov_b64 s[30:31], 0x40000
	s_andn2_b64 vcc, exec, s[38:39]
	s_waitcnt vmcnt(7)
	v_pk_fma_f32 v[140:141], v[140:141], v[108:109], v[176:177]
	v_lshl_add_u64 v[176:177], s[28:29], 0, v[170:171]
	v_lshl_add_u64 v[176:177], v[176:177], 0, v[166:167]
	v_pk_fma_f32 v[126:127], v[126:127], v[70:71], v[198:199]
	v_pk_fma_f32 v[124:125], v[124:125], v[68:69], v[196:197]
	global_store_dwordx4 v[176:177], v[124:127], off offset:512
	v_pk_fma_f32 v[122:123], v[122:123], v[66:67], v[202:203]
	v_pk_fma_f32 v[120:121], v[120:121], v[64:65], v[200:201]
	v_lshl_add_u64 v[124:125], s[28:29], 0, v[180:181]
	global_store_dwordx4 v[176:177], v[120:123], off offset:576
	v_lshl_add_u64 v[124:125], v[124:125], 0, v[166:167]
	v_pk_fma_f32 v[142:143], v[142:143], v[110:111], v[178:179]
	v_pk_fma_f32 v[122:123], v[134:135], v[110:111], v[206:207]
	v_pk_fma_f32 v[120:121], v[132:133], v[108:109], v[204:205]
	v_pk_fma_f32 v[138:139], v[138:139], v[74:75], v[194:195]
	v_pk_fma_f32 v[136:137], v[136:137], v[72:73], v[192:193]
	global_store_dwordx4 v[124:125], v[120:123], off
	v_pk_fma_f32 v[118:119], v[118:119], v[70:71], v[214:215]
	v_pk_fma_f32 v[116:117], v[116:117], v[68:69], v[212:213]
	v_pk_fma_f32 v[122:123], v[130:131], v[74:75], v[210:211]
	v_pk_fma_f32 v[120:121], v[128:129], v[72:73], v[208:209]
	v_pk_fma_f32 v[114:115], v[114:115], v[66:67], v[218:219]
	v_pk_fma_f32 v[112:113], v[112:113], v[64:65], v[216:217]
	global_store_dwordx4 v[176:177], v[140:143], off
	global_store_dwordx4 v[176:177], v[136:139], off offset:64
	global_store_dwordx4 v[124:125], v[120:123], off offset:64
	global_store_dwordx4 v[124:125], v[116:119], off offset:512
	global_store_dwordx4 v[124:125], v[112:115], off offset:576
	v_lshl_add_u64 v[176:177], v[170:171], 0, s[30:31]
	v_lshl_add_u64 v[124:125], v[168:169], 0, v[176:177]
	s_mov_b64 s[30:31], 0x60000
	s_nop 0
	s_nop 0
	s_nop 0
	s_nop 0
	s_nop 0
	v_lshl_add_u64 v[178:179], v[170:171], 0, s[30:31]
	v_lshl_add_u64 v[140:141], v[168:169], 0, v[178:179]
	s_nop 0
	s_nop 0
	s_nop 0
	s_nop 0
	s_waitcnt vmcnt(8)
;     __device__ __forceinline__ void operator()(const Acc& acc, const Unit& u, int wr, int wc, int fr, int fq) const {
;     ...
;         for (int aim = 0; aim < 4; ++aim) { const int ai = aim >> 1, m0 = (aim & 1) * 2;
;             f32x4 bs[2][2][2];
; #pragma unroll
;             for (int mm = 0; mm < 2; ++mm) { const size_t off = (size_t)(row0 + ai * HALF + (m0 + mm) * 16) * D + col0;
; #pragma unroll
;                 for (int bj = 0; bj < 2; ++bj)
; #pragma unroll
;                     for (int n = 0; n < 2; ++n) bs[mm][bj][n] = *(const f32x4*)(base + off + bj * HALF + n * 16); }
; #pragma unroll
;             for (int mm = 0; mm < 2; ++mm) { const size_t off = (size_t)(row0 + ai * HALF + (m0 + mm) * 16) * D + col0;
; #pragma unroll
;                 for (int bj = 0; bj < 2; ++bj)
; #pragma unroll
;                     for (int n = 0; n < 2; ++n) *(f32x4*)(out + off + bj * HALF + n * 16) = bs[mm][bj][n] + gv[bj][n] * acc[ai][bj][m0 + mm][n]; }
;             asm volatile("" ::: "memory"); }
	v_mov_b32_e32 v112, v220
	v_mov_b32_e32 v113, v221
	v_mov_b32_e32 v114, v222
	v_mov_b32_e32 v115, v223
	v_mov_b32_e32 v116, v224
	v_mov_b32_e32 v117, v225
	v_mov_b32_e32 v118, v226
	v_mov_b32_e32 v119, v227
	v_mov_b32_e32 v120, v228
	v_mov_b32_e32 v121, v229
	v_mov_b32_e32 v122, v230
	v_mov_b32_e32 v123, v231
	v_mov_b32_e32 v124, v232
	v_mov_b32_e32 v125, v233
	v_mov_b32_e32 v126, v234
	v_mov_b32_e32 v127, v235
	v_mov_b32_e32 v128, v236
	v_mov_b32_e32 v129, v237
	v_mov_b32_e32 v130, v238
	v_mov_b32_e32 v131, v239
	v_mov_b32_e32 v132, v240
	v_mov_b32_e32 v133, v241
	v_mov_b32_e32 v134, v242
	v_mov_b32_e32 v135, v243
	v_mov_b32_e32 v136, v250
	v_mov_b32_e32 v137, v251
	v_mov_b32_e32 v138, v252
	v_mov_b32_e32 v139, v253
	global_load_dwordx4 v[140:143], v[140:141], off offset:576
	v_mov_b32_e32 v254, 0x100000
	v_mov_b32_e32 v255, 0
	v_lshl_add_u64 v[232:233], v[170:171], 0, v[254:255]
	v_lshl_add_u64 v[232:233], v[168:169], 0, v[232:233]
	global_load_dwordx4 v[220:223], v[232:233], off
	global_load_dwordx4 v[224:227], v[232:233], off offset:64
	global_load_dwordx4 v[228:231], v[232:233], off offset:512
	s_nop 0
	global_load_dwordx4 v[232:235], v[232:233], off offset:576
	v_mov_b32_e32 v254, 0x120000
	v_lshl_add_u64 v[250:251], v[170:171], 0, v[254:255]
	v_lshl_add_u64 v[250:251], v[168:169], 0, v[250:251]
	global_load_dwordx4 v[236:239], v[250:251], off
	global_load_dwordx4 v[240:243], v[250:251], off offset:64
	s_nop 0
	global_load_dwordx4 v[250:253], v[250:251], off offset:512
	s_mov_b64 s[30:31], 0x100000
	s_nop 0
	v_pk_fma_f32 v[104:105], v[104:105], v[108:109], v[112:113]
	v_lshl_add_u64 v[112:113], s[28:29], 0, v[176:177]
	v_lshl_add_u64 v[112:113], v[112:113], 0, v[166:167]
	s_nop 0
	v_pk_fma_f32 v[90:91], v[90:91], v[70:71], v[122:123]
	v_pk_fma_f32 v[88:89], v[88:89], v[68:69], v[120:121]
	global_store_dwordx4 v[112:113], v[88:91], off offset:512
	s_nop 0
	v_pk_fma_f32 v[86:87], v[86:87], v[66:67], v[126:127]
	v_pk_fma_f32 v[84:85], v[84:85], v[64:65], v[124:125]
	v_lshl_add_u64 v[88:89], s[28:29], 0, v[178:179]
	global_store_dwordx4 v[112:113], v[84:87], off offset:576
	v_lshl_add_u64 v[88:89], v[88:89], 0, v[166:167]
	v_pk_fma_f32 v[106:107], v[106:107], v[110:111], v[114:115]
	s_nop 0
	v_pk_fma_f32 v[86:87], v[98:99], v[110:111], v[130:131]
	v_pk_fma_f32 v[84:85], v[96:97], v[108:109], v[128:129]
	v_pk_fma_f32 v[102:103], v[102:103], v[74:75], v[118:119]
	v_pk_fma_f32 v[100:101], v[100:101], v[72:73], v[116:117]
	global_store_dwordx4 v[88:89], v[84:87], off
	s_nop 0
	v_pk_fma_f32 v[82:83], v[82:83], v[70:71], v[138:139]
	v_pk_fma_f32 v[80:81], v[80:81], v[68:69], v[136:137]
	v_pk_fma_f32 v[86:87], v[94:95], v[74:75], v[134:135]
	v_pk_fma_f32 v[84:85], v[92:93], v[72:73], v[132:133]
	s_waitcnt vmcnt(10)
	v_pk_fma_f32 v[78:79], v[78:79], v[66:67], v[142:143]
	v_pk_fma_f32 v[76:77], v[76:77], v[64:65], v[140:141]
	global_store_dwordx4 v[112:113], v[104:107], off
	global_store_dwordx4 v[112:113], v[100:103], off offset:64
	global_store_dwordx4 v[88:89], v[84:87], off offset:64
	global_store_dwordx4 v[88:89], v[80:83], off offset:512
	global_store_dwordx4 v[88:89], v[76:79], off offset:576
	v_lshl_add_u64 v[112:113], v[170:171], 0, s[30:31]
	v_lshl_add_u64 v[88:89], v[168:169], 0, v[112:113]
	s_mov_b64 s[30:31], 0x120000
	s_nop 0
	s_nop 0
	s_nop 0
	s_nop 0
	s_nop 0
	v_lshl_add_u64 v[114:115], v[170:171], 0, s[30:31]
	v_lshl_add_u64 v[104:105], v[168:169], 0, v[114:115]
	s_nop 0
	s_nop 0
	s_nop 0
	s_nop 0
	s_waitcnt vmcnt(8)
; #define PG8_BAR __builtin_amdgcn_s_barrier()
; template <class Epi, class Map>
; __device__ __forceinline__ void gemm_phase(LAS unsigned char* lds, const Gemm g, const Sched<Map>& S, const Epi& E) {
;     ...
;         if (wr == 0) PG8_BAR;
;         E(acc, cur, wr, wc, fr, fq);
;         if (!has_next) break;
; #pragma unroll
;         for (int a = 0; a < 2; ++a)
; #pragma unroll
;             for (int b = 0; b < 2; ++b)
; #pragma unroll
;                 for (int m = 0; m < 4; ++m)
; #pragma unroll
;                     for (int n = 0; n < 2; ++n) acc[a][b][m][n] = (f32x4){0.f, 0.f, 0.f, 0.f};
;         cur = nxt; cA = nA; cB = nB; ++ui;
;         if (wr == 1) PG8_BAR;
;     __device__ __forceinline__ void operator()(const Acc& acc, const Unit& u, int wr, int wc, int fr, int fq) const {
;     ...
;         for (int aim = 0; aim < 4; ++aim) { const int ai = aim >> 1, m0 = (aim & 1) * 2;
;             f32x4 bs[2][2][2];
; #pragma unroll
;             for (int mm = 0; mm < 2; ++mm) { const size_t off = (size_t)(row0 + ai * HALF + (m0 + mm) * 16) * D + col0;
; #pragma unroll
;                 for (int bj = 0; bj < 2; ++bj)
; #pragma unroll
;                     for (int n = 0; n < 2; ++n) bs[mm][bj][n] = *(const f32x4*)(base + off + bj * HALF + n * 16); }
; #pragma unroll
;             for (int mm = 0; mm < 2; ++mm) { const size_t off = (size_t)(row0 + ai * HALF + (m0 + mm) * 16) * D + col0;
; #pragma unroll
;                 for (int bj = 0; bj < 2; ++bj)
; #pragma unroll
;                     for (int n = 0; n < 2; ++n) *(f32x4*)(out + off + bj * HALF + n * 16) = bs[mm][bj][n] + gv[bj][n] * acc[ai][bj][m0 + mm][n]; }
;             asm volatile("" ::: "memory"); }
	v_mov_b32_e32 v76, v220
	v_mov_b32_e32 v77, v221
	v_mov_b32_e32 v78, v222
	v_mov_b32_e32 v79, v223
	v_mov_b32_e32 v80, v224
	v_mov_b32_e32 v81, v225
	v_mov_b32_e32 v82, v226
	v_mov_b32_e32 v83, v227
	v_mov_b32_e32 v84, v228
	v_mov_b32_e32 v85, v229
	v_mov_b32_e32 v86, v230
	v_mov_b32_e32 v87, v231
	v_mov_b32_e32 v88, v232
	v_mov_b32_e32 v89, v233
	v_mov_b32_e32 v90, v234
	v_mov_b32_e32 v91, v235
	v_mov_b32_e32 v92, v236
	v_mov_b32_e32 v93, v237
	v_mov_b32_e32 v94, v238
	v_mov_b32_e32 v95, v239
	v_mov_b32_e32 v96, v240
	v_mov_b32_e32 v97, v241
	v_mov_b32_e32 v98, v242
	v_mov_b32_e32 v99, v243
	v_mov_b32_e32 v100, v250
	v_mov_b32_e32 v101, v251
	v_mov_b32_e32 v102, v252
	v_mov_b32_e32 v103, v253
	global_load_dwordx4 v[104:107], v[104:105], off offset:576
	v_mov_b32_e32 v254, 0x140000
	v_mov_b32_e32 v255, 0
	v_lshl_add_u64 v[232:233], v[170:171], 0, v[254:255]
	v_lshl_add_u64 v[232:233], v[168:169], 0, v[232:233]
	global_load_dwordx4 v[220:223], v[232:233], off
	global_load_dwordx4 v[224:227], v[232:233], off offset:64
	global_load_dwordx4 v[228:231], v[232:233], off offset:512
	s_nop 0
	global_load_dwordx4 v[232:235], v[232:233], off offset:576
	v_mov_b32_e32 v254, 0x160000
	v_lshl_add_u64 v[250:251], v[170:171], 0, v[254:255]
	v_lshl_add_u64 v[250:251], v[168:169], 0, v[250:251]
	global_load_dwordx4 v[236:239], v[250:251], off
	global_load_dwordx4 v[240:243], v[250:251], off offset:64
	s_nop 0
	global_load_dwordx4 v[250:253], v[250:251], off offset:512
	s_mov_b64 s[30:31], 0x140000
	s_nop 0
	v_pk_fma_f32 v[60:61], v[60:61], v[108:109], v[76:77]
	v_lshl_add_u64 v[76:77], s[28:29], 0, v[112:113]
	v_lshl_add_u64 v[76:77], v[76:77], 0, v[166:167]
	s_nop 0
	v_pk_fma_f32 v[46:47], v[46:47], v[70:71], v[86:87]
	v_pk_fma_f32 v[44:45], v[44:45], v[68:69], v[84:85]
	global_store_dwordx4 v[76:77], v[44:47], off offset:512
	s_nop 0
	v_pk_fma_f32 v[42:43], v[42:43], v[66:67], v[90:91]
	v_pk_fma_f32 v[40:41], v[40:41], v[64:65], v[88:89]
	v_lshl_add_u64 v[44:45], s[28:29], 0, v[114:115]
	global_store_dwordx4 v[76:77], v[40:43], off offset:576
	v_lshl_add_u64 v[44:45], v[44:45], 0, v[166:167]
	v_pk_fma_f32 v[62:63], v[62:63], v[110:111], v[78:79]
	s_nop 0
	v_pk_fma_f32 v[42:43], v[54:55], v[110:111], v[94:95]
	v_pk_fma_f32 v[40:41], v[52:53], v[108:109], v[92:93]
	v_pk_fma_f32 v[58:59], v[58:59], v[74:75], v[82:83]
	v_pk_fma_f32 v[56:57], v[56:57], v[72:73], v[80:81]
	global_store_dwordx4 v[44:45], v[40:43], off
	s_nop 0
	v_pk_fma_f32 v[38:39], v[38:39], v[70:71], v[102:103]
	v_pk_fma_f32 v[36:37], v[36:37], v[68:69], v[100:101]
	v_pk_fma_f32 v[42:43], v[50:51], v[74:75], v[98:99]
	v_pk_fma_f32 v[40:41], v[48:49], v[72:73], v[96:97]
	s_waitcnt vmcnt(10)
	v_pk_fma_f32 v[34:35], v[34:35], v[66:67], v[106:107]
	v_pk_fma_f32 v[32:33], v[32:33], v[64:65], v[104:105]
	global_store_dwordx4 v[76:77], v[60:63], off
	global_store_dwordx4 v[76:77], v[56:59], off offset:64
	global_store_dwordx4 v[44:45], v[40:43], off offset:64
	global_store_dwordx4 v[44:45], v[36:39], off offset:512
	global_store_dwordx4 v[44:45], v[32:35], off offset:576
	v_lshl_add_u64 v[76:77], v[170:171], 0, s[30:31]
	s_mov_b64 s[30:31], 0x160000
	v_lshl_add_u64 v[44:45], v[168:169], 0, v[76:77]
	v_lshl_add_u64 v[78:79], v[170:171], 0, s[30:31]
	s_nop 0
	s_nop 0
	s_nop 0
	s_nop 0
	s_nop 0
	v_lshl_add_u64 v[60:61], v[168:169], 0, v[78:79]
	s_nop 0
	s_nop 0
	s_nop 0
	s_nop 0
	s_waitcnt vmcnt(8)
	v_mov_b32_e32 v32, v220
	v_mov_b32_e32 v33, v221
	v_mov_b32_e32 v34, v222
	v_mov_b32_e32 v35, v223
	v_mov_b32_e32 v36, v224
	v_mov_b32_e32 v37, v225
	v_mov_b32_e32 v38, v226
	v_mov_b32_e32 v39, v227
	v_mov_b32_e32 v40, v228
	v_mov_b32_e32 v41, v229
	v_mov_b32_e32 v42, v230
	v_mov_b32_e32 v43, v231
	v_mov_b32_e32 v44, v232
	v_mov_b32_e32 v45, v233
	v_mov_b32_e32 v46, v234
	v_mov_b32_e32 v47, v235
	v_mov_b32_e32 v48, v236
	v_mov_b32_e32 v49, v237
	v_mov_b32_e32 v50, v238
	v_mov_b32_e32 v51, v239
	v_mov_b32_e32 v52, v240
	v_mov_b32_e32 v53, v241
	v_mov_b32_e32 v54, v242
	v_mov_b32_e32 v55, v243
	v_mov_b32_e32 v56, v250
	v_mov_b32_e32 v57, v251
	v_mov_b32_e32 v58, v252
	v_mov_b32_e32 v59, v253
	global_load_dwordx4 v[60:63], v[60:61], off offset:576
	s_waitcnt vmcnt(7)
	v_pk_fma_f32 v[28:29], v[28:29], v[108:109], v[32:33]
	v_lshl_add_u64 v[32:33], s[28:29], 0, v[76:77]
	v_lshl_add_u64 v[32:33], v[32:33], 0, v[166:167]
	s_waitcnt vmcnt(5)
	v_pk_fma_f32 v[18:19], v[18:19], v[70:71], v[42:43]
	v_pk_fma_f32 v[16:17], v[16:17], v[68:69], v[40:41]
	global_store_dwordx4 v[32:33], v[16:19], off offset:512
	s_waitcnt vmcnt(5)
	v_pk_fma_f32 v[14:15], v[14:15], v[66:67], v[46:47]
	v_pk_fma_f32 v[12:13], v[12:13], v[64:65], v[44:45]
	v_lshl_add_u64 v[16:17], s[28:29], 0, v[78:79]
	v_pk_fma_f32 v[30:31], v[30:31], v[110:111], v[34:35]
	v_pk_fma_f32 v[26:27], v[26:27], v[74:75], v[38:39]
	v_pk_fma_f32 v[24:25], v[24:25], v[72:73], v[36:37]
	global_store_dwordx4 v[32:33], v[12:15], off offset:576
	v_lshl_add_u64 v[16:17], v[16:17], 0, v[166:167]
	s_waitcnt vmcnt(4)
	v_pk_fma_f32 v[10:11], v[10:11], v[74:75], v[54:55]
	v_pk_fma_f32 v[14:15], v[22:23], v[110:111], v[50:51]
	v_pk_fma_f32 v[12:13], v[20:21], v[108:109], v[48:49]
	v_pk_fma_f32 v[8:9], v[8:9], v[72:73], v[52:53]
	s_waitcnt vmcnt(3)
	v_pk_fma_f32 v[6:7], v[6:7], v[70:71], v[58:59]
	v_pk_fma_f32 v[4:5], v[4:5], v[68:69], v[56:57]
	s_waitcnt vmcnt(2)
	v_pk_fma_f32 v[2:3], v[2:3], v[66:67], v[62:63]
	v_pk_fma_f32 v[0:1], v[0:1], v[64:65], v[60:61]
	global_store_dwordx4 v[32:33], v[28:31], off
	global_store_dwordx4 v[32:33], v[24:27], off offset:64
	global_store_dwordx4 v[16:17], v[12:15], off
	global_store_dwordx4 v[16:17], v[8:11], off offset:64
	global_store_dwordx4 v[16:17], v[4:7], off offset:512
	global_store_dwordx4 v[16:17], v[0:3], off offset:576
	s_mov_b64 s[28:29], -1
	s_cbranch_vccnz .LBB0_1175
	s_andn2_b64 vcc, exec, s[16:17]
	s_cbranch_vccnz .LBB0_1174
	s_barrier
	s_branch .LBB0_1174

; __global__ void __launch_bounds__(NT, 2) fwd_megakernel(Args a) {
;     extern __shared__ __attribute__((aligned(16))) unsigned char lds_raw[];
	.amdhsa_kernel _Z14fwd_megakernel4Args
		.amdhsa_group_segment_fixed_size 16384
		.amdhsa_private_segment_fixed_size 0
		.amdhsa_kernarg_size 992
		.amdhsa_user_sgpr_count 2
		.amdhsa_user_sgpr_dispatch_ptr 0
		.amdhsa_user_sgpr_queue_ptr 0
		.amdhsa_user_sgpr_kernarg_segment_ptr 1
		.amdhsa_user_sgpr_dispatch_id 0
		.amdhsa_user_sgpr_kernarg_preload_length 0
		.amdhsa_user_sgpr_kernarg_preload_offset 0
		.amdhsa_user_sgpr_private_segment_size 0
		.amdhsa_uses_dynamic_stack 0
		.amdhsa_enable_private_segment 0
		.amdhsa_system_sgpr_workgroup_id_x 1
		.amdhsa_system_sgpr_workgroup_id_y 0
		.amdhsa_system_sgpr_workgroup_id_z 0
		.amdhsa_system_sgpr_workgroup_info 0
		.amdhsa_system_vgpr_workitem_id 2
		.amdhsa_next_free_vgpr 256
		.amdhsa_next_free_sgpr 100
		.amdhsa_accum_offset 256
		.amdhsa_reserve_vcc 1
		.amdhsa_float_round_mode_32 0
		.amdhsa_float_round_mode_16_64 0
		.amdhsa_float_denorm_mode_32 3
		.amdhsa_float_denorm_mode_16_64 3
		.amdhsa_dx10_clamp 1
		.amdhsa_ieee_mode 1
		.amdhsa_fp16_overflow 0
		.amdhsa_tg_split 0
		.amdhsa_exception_fp_ieee_invalid_op 0
		.amdhsa_exception_fp_denorm_src 0
		.amdhsa_exception_fp_ieee_div_zero 0
		.amdhsa_exception_fp_ieee_overflow 0
		.amdhsa_exception_fp_ieee_underflow 0
		.amdhsa_exception_fp_ieee_inexact 0
		.amdhsa_exception_int_div_zero 0
	.end_amdhsa_kernel

; __global__ void __launch_bounds__(NT, 2) fwd_megakernel(Args a) {
;     extern __shared__ __attribute__((aligned(16))) unsigned char lds_raw[];
amdhsa.kernels:
  - .agpr_count:     0
    .args:
      - .offset:         0
        .size:           736
        .value_kind:     by_value
      - .offset:         736
        .size:           4
        .value_kind:     hidden_block_count_x
      - .offset:         740
        .size:           4
        .value_kind:     hidden_block_count_y
      - .offset:         744
        .size:           4
        .value_kind:     hidden_block_count_z
      - .offset:         748
        .size:           2
        .value_kind:     hidden_group_size_x
      - .offset:         750
        .size:           2
        .value_kind:     hidden_group_size_y
      - .offset:         752
        .size:           2
        .value_kind:     hidden_group_size_z
      - .offset:         754
        .size:           2
        .value_kind:     hidden_remainder_x
      - .offset:         756
        .size:           2
        .value_kind:     hidden_remainder_y
      - .offset:         758
        .size:           2
        .value_kind:     hidden_remainder_z
      - .offset:         776
        .size:           8
        .value_kind:     hidden_global_offset_x
      - .offset:         784
        .size:           8
        .value_kind:     hidden_global_offset_y
      - .offset:         792
        .size:           8
        .value_kind:     hidden_global_offset_z
      - .offset:         800
        .size:           2
        .value_kind:     hidden_grid_dims
      - .offset:         824
        .size:           8
        .value_kind:     hidden_multigrid_sync_arg
      - .offset:         856
        .size:           4
        .value_kind:     hidden_dynamic_lds_size
    .group_segment_fixed_size: 16384
    .kernarg_segment_align: 8
    .kernarg_segment_size: 992
    .language:       OpenCL C
    .language_version:
      - 2
      - 0
    .max_flat_workgroup_size: 512
    .name:           _Z14fwd_megakernel4Args
    .private_segment_fixed_size: 0
    .sgpr_count:     106
    .sgpr_spill_count: 305
    .symbol:         _Z14fwd_megakernel4Args.kd
    .uniform_work_group_size: 1
    .uses_dynamic_stack: false
    .vgpr_count:     256
    .vgpr_spill_count: 0
    .wavefront_size: 64
